# group barriers: L1 invalidate issued right after the arrive (before polling) so that it overlaps the wait; no loads of shared data happen between it and the barrier exit
# baseline (speedup 1.0000x reference)
; __device__ __forceinline__ void grid_barrier(unsigned* ctr, unsigned target) {
;     asm volatile("s_waitcnt vmcnt(0)" ::: "memory");
;     __syncthreads();
;     if (threadIdx.x == 0) {
;         __builtin_amdgcn_fence(__ATOMIC_RELEASE, "agent");
;         asm volatile("s_waitcnt vmcnt(0)" ::: "memory");
;         __hip_atomic_fetch_add(ctr, 1u, __ATOMIC_RELAXED, __HIP_MEMORY_SCOPE_AGENT);
;         while (__hip_atomic_load(ctr, __ATOMIC_RELAXED, __HIP_MEMORY_SCOPE_AGENT) < target) __builtin_amdgcn_s_sleep(1);
;         __builtin_amdgcn_fence(__ATOMIC_ACQUIRE, "agent");
;         asm volatile("s_waitcnt vmcnt(0)" ::: "memory");
;     }
;     __syncthreads();
; }
.LBB0_111:
	s_or_b64 exec, exec, s[4:5]
	buffer_inv sc1
	v_mov_b32_e32 v0, 0
	s_nop 1
	global_load_dword v1, v0, s[10:11] offset:256 sc1
	s_waitcnt vmcnt(0)
	v_cmp_le_u32_e32 vcc, s8, v1
	s_cbranch_vccnz .LBB0_114
	v_readlane_b32 s2, v254, 0
	v_readlane_b32 s3, v254, 1

; __device__ __forceinline__ void grid_barrier(unsigned* ctr, unsigned target) {
;     asm volatile("s_waitcnt vmcnt(0)" ::: "memory");
;     __syncthreads();
;     if (threadIdx.x == 0) {
;         __builtin_amdgcn_fence(__ATOMIC_RELEASE, "agent");
;         asm volatile("s_waitcnt vmcnt(0)" ::: "memory");
;         __hip_atomic_fetch_add(ctr, 1u, __ATOMIC_RELAXED, __HIP_MEMORY_SCOPE_AGENT);
;         while (__hip_atomic_load(ctr, __ATOMIC_RELAXED, __HIP_MEMORY_SCOPE_AGENT) < target) __builtin_amdgcn_s_sleep(1);
;         __builtin_amdgcn_fence(__ATOMIC_ACQUIRE, "agent");
;         asm volatile("s_waitcnt vmcnt(0)" ::: "memory");
;     }
;     __syncthreads();
; }
.LBB0_114:
	s_waitcnt vmcnt(0)
	global_load_dword v1, v0, s[10:11] offset:260 sc1
	global_load_dword v2, v0, s[10:11] offset:264 sc1
	s_waitcnt vmcnt(0)
	v_add_u32_e32 v1, v1, v2
	s_nop 0
	v_readfirstlane_b32 s98, v1

; __device__ __forceinline__ void grid_barrier(unsigned* ctr, unsigned target) {
;     asm volatile("s_waitcnt vmcnt(0)" ::: "memory");
;     __syncthreads();
;     if (threadIdx.x == 0) {
;         __builtin_amdgcn_fence(__ATOMIC_RELEASE, "agent");
;         asm volatile("s_waitcnt vmcnt(0)" ::: "memory");
;         __hip_atomic_fetch_add(ctr, 1u, __ATOMIC_RELAXED, __HIP_MEMORY_SCOPE_AGENT);
;         while (__hip_atomic_load(ctr, __ATOMIC_RELAXED, __HIP_MEMORY_SCOPE_AGENT) < target) __builtin_amdgcn_s_sleep(1);
;         __builtin_amdgcn_fence(__ATOMIC_ACQUIRE, "agent");
;         asm volatile("s_waitcnt vmcnt(0)" ::: "memory");
;     }
;     __syncthreads();
; }
.LBB0_249:
	s_or_b64 exec, exec, s[8:9]
	buffer_inv sc1
	s_nop 2
	global_load_dword v0, v1, s[12:13] offset:256 sc1
	v_readlane_b32 s8, v254, 62
	s_mov_b64 s[6:7], s[12:13]
	s_waitcnt vmcnt(0)
	v_cmp_le_u32_e32 vcc, s8, v0
	s_cbranch_vccnz .LBB0_251
.LBB0_250:
	s_sleep 1
	global_load_dword v0, v1, s[6:7] offset:256 sc1
	s_waitcnt vmcnt(0)
	v_cmp_gt_u32_e32 vcc, s8, v0
	s_cbranch_vccnz .LBB0_250
.LBB0_251:
	s_waitcnt vmcnt(0)
.LBB0_252:
	s_or_b64 exec, exec, s[4:5]
	v_mov_b32_e32 v210, v234
	v_readfirstlane_b32 s4, v234
	s_nop 0
	s_cmpk_lt_u32 s4, 0x100
	s_cbranch_scc1 .Lattn_prio_skip
	s_setprio 1

; __device__ __forceinline__ void grid_barrier(unsigned* ctr, unsigned target) {
;     asm volatile("s_waitcnt vmcnt(0)" ::: "memory");
;     __syncthreads();
;     if (threadIdx.x == 0) {
;         __builtin_amdgcn_fence(__ATOMIC_RELEASE, "agent");
;         asm volatile("s_waitcnt vmcnt(0)" ::: "memory");
;         __hip_atomic_fetch_add(ctr, 1u, __ATOMIC_RELAXED, __HIP_MEMORY_SCOPE_AGENT);
;         while (__hip_atomic_load(ctr, __ATOMIC_RELAXED, __HIP_MEMORY_SCOPE_AGENT) < target) __builtin_amdgcn_s_sleep(1);
;         __builtin_amdgcn_fence(__ATOMIC_ACQUIRE, "agent");
;         asm volatile("s_waitcnt vmcnt(0)" ::: "memory");
;     }
;     __syncthreads();
; }
.LBB0_765:
	s_or_b64 exec, exec, s[8:9]
	buffer_inv sc1
	s_nop 2
	global_load_dword v0, v1, s[12:13] offset:256 sc1
	s_mov_b64 s[6:7], s[12:13]
	s_waitcnt vmcnt(0)
	v_cmp_le_u32_e32 vcc, s44, v0
	s_cbranch_vccnz .LBB0_767
.LBB0_766:
	s_sleep 1
	global_load_dword v0, v1, s[6:7] offset:256 sc1
	s_waitcnt vmcnt(0)
	v_cmp_gt_u32_e32 vcc, s44, v0
	s_cbranch_vccnz .LBB0_766
.LBB0_767:
	s_waitcnt vmcnt(0)
.LBB0_768:
	s_or_b64 exec, exec, s[4:5]
	s_cmp_lg_u32 s68, 3
	s_cselect_b64 s[6:7], -1, 0
	s_cmp_lg_u32 s68, 0
	s_mov_b32 s40, 0
	s_cselect_b64 s[8:9], -1, 0
	s_add_i32 s33, s68, 1
	s_barrier
	s_cmp_lt_i32 s40, 1
	s_mov_b64 s[4:5], -1
	s_cbranch_scc1 .LBB0_788

; __device__ __forceinline__ void grid_barrier(unsigned* ctr, unsigned target) {
;     asm volatile("s_waitcnt vmcnt(0)" ::: "memory");
;     __syncthreads();
;     if (threadIdx.x == 0) {
;         __builtin_amdgcn_fence(__ATOMIC_RELEASE, "agent");
;         asm volatile("s_waitcnt vmcnt(0)" ::: "memory");
;         __hip_atomic_fetch_add(ctr, 1u, __ATOMIC_RELAXED, __HIP_MEMORY_SCOPE_AGENT);
;         while (__hip_atomic_load(ctr, __ATOMIC_RELAXED, __HIP_MEMORY_SCOPE_AGENT) < target) __builtin_amdgcn_s_sleep(1);
;         __builtin_amdgcn_fence(__ATOMIC_ACQUIRE, "agent");
;         asm volatile("s_waitcnt vmcnt(0)" ::: "memory");
;     }
;     __syncthreads();
; }
.LBB0_802:
	s_or_b64 exec, exec, s[12:13]
	buffer_inv sc1
	s_nop 2
	global_load_dword v0, v1, s[16:17] offset:256 sc1
	s_mov_b64 s[10:11], s[16:17]
	s_waitcnt vmcnt(0)
	v_cmp_le_u32_e32 vcc, s44, v0
	s_cbranch_vccnz .LBB0_804
.LBB0_803:
	s_sleep 1
	global_load_dword v0, v1, s[10:11] offset:256 sc1
	s_waitcnt vmcnt(0)
	v_cmp_gt_u32_e32 vcc, s44, v0
	s_cbranch_vccnz .LBB0_803
.LBB0_804:
	s_waitcnt vmcnt(0)
.LBB0_805:
	s_or_b64 exec, exec, s[4:5]
	s_barrier
